# GEMM phases P4/P11/P7: workgroups with one unit fewer start staggered by 1/3, 2/3 (1/2) unit time to desynchronize epilogue store bursts
# baseline (speedup 1.0000x reference)
.LBB0_34:
	s_mov_b32 s0, 0
	s_cmp_eq_u32 s85, 4
	s_cselect_b32 s1, 1, 0
	s_cmp_eq_u32 s85, 11
	s_cselect_b32 s1, 1, s1
	s_cmp_lg_u32 s1, 0
	s_cbranch_scc0 .Lstg_p7
	s_cmpk_ge_u32 s66, 88
	s_cselect_b32 s0, 4, 0
	s_cmpk_ge_u32 s66, 172
	s_cselect_b32 s0, 8, s0
	s_branch .Lstg_go
.Lstg_p7:
	s_cmp_eq_u32 s85, 7
	s_cbranch_scc0 .Lstg_done
	s_cmpk_ge_u32 s66, 180
	s_cselect_b32 s0, 6, 0
.Lstg_go:
	s_cmp_eq_u32 s0, 0
	s_cbranch_scc1 .Lstg_done
.Lstg_loop:
	s_sleep 80
	s_add_i32 s0, s0, -1
	s_cmp_lg_u32 s0, 0
	s_cbranch_scc1 .Lstg_loop
